# static s_setprio 1 for waves 4-7 during the NSA phase (two waves per SIMD run the same barrier-delimited tile loop)
# baseline (speedup 1.0000x reference)
; #define LAS __attribute__((address_space(3)))
; __device__ __forceinline__ void nsa_unit(const Args& a, int l, int b, int qi, float bnd0, float bnd1, float bnd2, LAS unsigned char* lds, int tid, int lane, int wave) {
;     LAS bf16_t* KVB = (LAS bf16_t*)lds;
;     LAS float* IMP = (LAS float*)(lds + 37888);
;     LAS unsigned long long* SELM = (LAS unsigned long long*)(lds + 104448);
;     LAS float* INVL = (LAS float*)(lds + 105024);
;     const bf16_t* QN = (const bf16_t*)(a.ws + WS_QN); const float* GATES = (const float*)(a.ws + WS_GATES); bf16_t* Y = (bf16_t*)(a.ws + WS_Y);
;     const int fr = lane & 15, fq = lane >> 4, h = wave >> 1, qbase = (wave & 1) * 32;
;     const size_t t0 = (size_t)b * SEQ + 64 * qi;
;     const float slope2 = LOG2E * exp2f(-2.0f * (float)(h + 1));
;     bf16x8 qf[2][2]; float gate[2][3];
; #pragma unroll
;     for (int mt = 0; mt < 2; ++mt) { const size_t t = t0 + qbase + 16 * mt + fr;
; #pragma unroll
;         for (int ks = 0; ks < 2; ++ks) qf[mt][ks] = *(const bf16x8*)(QN + t * 256 + h * 64 + 32 * ks + 8 * fq);
; #pragma unroll
;         for (int br = 0; br < 3; ++br) gate[mt][br] = GATES[t * 12 + h * 3 + br]; }
; __device__ __forceinline__ void nsa_phase(const Args& a, int l, int qslot, LAS unsigned char* lds, int tid, int lane, int wave) {
;     unsigned* ctr = (unsigned*)(a.ws + WS_CTL) + 64 * qslot;
;     LAS int* slot = (LAS int*)(lds + 106048);
;     const float qmx = wave_max64(fabsf(INTAB(a)[20][l * 64 + lane]));
;     const float bnd0 = 11.72f * qmx * wave_max64(fabsf(INTAB(a)[21][l * 192 + lane])), bnd1 = 11.72f * qmx * wave_max64(fabsf(INTAB(a)[21][l * 192 + 64 + lane])), bnd2 = 11.72f * qmx * wave_max64(fabsf(INTAB(a)[21][l * 192 + 128 + lane]));
.LBB0_128:
	s_waitcnt vmcnt(0)
	v_mov_b32_e32 v8, v228
	v_readlane_b32 s15, v252, 0
	v_readlane_b32 s38, v252, 13
	v_readlane_b32 s15, v254, 46
	v_readlane_b32 s39, v252, 14
	v_and_b32_e32 v0, 64, v234
	v_xor_b32_e32 v2, 1, v234
	v_add_u32_e32 v0, 64, v0
	s_waitcnt lgkmcnt(0)
	v_xor_b32_e32 v9, 2, v234
	global_load_dwordx4 v[10:13], v1, s[38:39]
	s_lshl_b32 s38, s9, 7
	v_cmp_lt_i32_e32 vcc, v2, v0
	v_xor_b32_e32 v14, 4, v234
	s_ashr_i32 s39, s38, 31
	v_readfirstlane_b32 s15, v8
	v_cndmask_b32_e32 v2, v234, v2, vcc
	v_cmp_lt_i32_e32 vcc, v9, v0
	v_xor_b32_e32 v15, 8, v234
	s_lshl_b64 s[38:39], s[38:39], 2
	v_cndmask_b32_e32 v9, v234, v9, vcc
	v_cmp_lt_i32_e32 vcc, v14, v0
	s_ashr_i32 s23, s15, 6
	s_cmp_gt_i32 s23, 3
	s_cbranch_scc0 .Lnsa_np
	s_setprio 1
.Lnsa_np:
	v_xor_b32_e32 v16, 16, v234
	v_and_b32_e32 v129, 63, v8
	v_cndmask_b32_e32 v18, v234, v14, vcc
	v_cmp_lt_i32_e32 vcc, v15, v0
	s_add_u32 s38, s72, s38
	v_xor_b32_e32 v17, 32, v234
	s_mul_i32 s40, s9, 0xc0
	v_cndmask_b32_e32 v19, v234, v15, vcc
	v_cmp_lt_i32_e32 vcc, v16, v0
	v_lshl_or_b32 v14, s9, 6, v129
	s_addc_u32 s39, s73, s39
	v_cndmask_b32_e32 v20, v234, v16, vcc
	v_cmp_lt_i32_e32 vcc, v17, v0
	v_or_b32_e32 v16, s40, v129
	v_ashrrev_i32_e32 v15, 31, v14
	v_writelane_b32 v255, s38, 9
	v_cndmask_b32_e32 v0, v234, v17, vcc
	v_ashrrev_i32_e32 v17, 31, v16
	v_writelane_b32 v255, s39, 10
	s_ashr_i32 s38, s40, 31
	s_movk_i32 s40, 0x1040
	v_cmp_gt_i32_e64 s[40:41], s40, v8
	v_ashrrev_i32_e32 v133, 3, v8
	v_lshlrev_b32_e32 v162, 2, v0
	v_writelane_b32 v255, s40, 11
	v_mov_b32_e32 v21, 0x980
	v_bfe_u32 v131, v8, 4, 2
	v_writelane_b32 v255, s41, 12
	s_movk_i32 s40, 0x48
	v_mul_lo_u32 v0, v133, s40
	s_movk_i32 s40, 0x90
	s_ashr_i32 s41, s15, 7
	v_lshlrev_b32_e32 v172, 1, v0
	s_add_i32 s44, s41, 1
	s_lshl_b32 s9, s23, 5
	s_mul_i32 s49, s41, 0x4100
	v_lshlrev_b32_e32 v9, 2, v9
	v_lshlrev_b32_e32 v18, 2, v18
	v_lshlrev_b32_e32 v19, 2, v19
	v_lshlrev_b32_e32 v139, 2, v20
	s_mul_i32 s46, s41, 3
	v_lshlrev_b32_e32 v22, 2, v129
	v_lshlrev_b32_e32 v20, 3, v131
	v_lshlrev_b32_e32 v164, 1, v133
	v_mov_b32_e32 v3, v1
	v_mov_b32_e32 v123, v1
	v_lshlrev_b32_e32 v128, 2, v131
	v_cmp_gt_u32_e64 s[42:43], 16, v129
	v_add_u32_e32 v186, 0xfffffe00, v8
	v_lshlrev_b32_e32 v188, 1, v20
	s_waitcnt vmcnt(0)
	v_lshl_add_u64 v[10:11], v[14:15], 2, v[10:11]
	flat_load_dword v14, v[10:11]
	v_lshl_add_u64 v[10:11], v[16:17], 2, v[12:13]
	v_mov_b32_e32 v17, s38
	flat_load_dword v15, v[10:11]
	v_lshl_add_u64 v[10:11], v[16:17], 2, v[12:13]
	flat_load_dword v12, v[10:11] offset:256
	v_and_b32_e32 v13, 15, v8
	flat_load_dword v10, v[10:11] offset:512
	v_lshlrev_b32_e32 v11, 3, v8
	v_lshlrev_b32_e32 v17, 2, v2
	v_and_b32_e32 v2, 56, v11
	v_mov_b32_e32 v11, 0x900
	v_mad_u32_u24 v166, v13, s40, v11
	v_mov_b32_e32 v11, 0x1200
	v_mad_u32_u24 v167, v13, s40, v11
	s_movk_i32 s40, 0x98
	v_lshlrev_b32_e32 v0, 1, v2
	v_mad_u32_u24 v169, v13, s40, v21
	v_mov_b32_e32 v21, 0x1300
	v_add3_u32 v175, 0, v172, v0
	v_cvt_f32_i32_e32 v0, s44
	v_or_b32_e32 v11, 48, v129
	v_mad_u32_u24 v170, v13, s40, v21
	v_lshlrev_b32_e32 v21, 6, v131
	v_mul_u32_u24_e32 v173, 0x90, v11
	v_mul_u32_u24_e32 v174, 0x98, v11
	v_sub_u32_e32 v11, v13, v21
	s_and_b32 s40, s9, 32
	v_or_b32_e32 v11, s40, v11
	v_subrev_u32_e32 v178, 31, v11
	v_mul_f32_e32 v11, -2.0, v0
	s_mov_b32 s44, 0xc2fc0000
	v_cmp_gt_f32_e32 vcc, s44, v11
	v_mov_b32_e32 v11, 0x42800000
	s_and_b64 s[44:45], vcc, exec
	v_cndmask_b32_e32 v11, 0, v11, vcc
	v_fmac_f32_e32 v11, -2.0, v0
	v_exp_f32_e32 v0, v11
	s_cselect_b32 s44, 0xffffffc0, 0
	s_add_i32 s45, s49, 0
	v_or_b32_e32 v130, s40, v13
	v_mov_b32_e32 v11, s45
	s_movk_i32 s45, 0x104
	v_ldexp_f32 v0, v0, s44
	v_mul_u32_u24_e32 v23, 0x4c, v2
	v_mad_u32_u24 v179, v130, s45, v11
	v_mul_f32_e32 v134, 0x3fb8aa3b, v0
	v_lshlrev_b32_e32 v176, 1, v23
	s_lshl_b32 s48, s41, 6
	s_lshl_b32 s41, s41, 8
	s_lshl_b32 s50, s40, 2
	s_add_i32 s41, s41, 0
	s_add_i32 s41, s41, s50
	s_add_i32 s41, s41, 0x19a40
	v_add_u32_e32 v180, s41, v22
	s_add_i32 s41, 0, 0x19800
	s_lshl_b32 s50, s23, 3
	s_lshl_b32 s40, s40, 3
	s_ashr_i32 s49, s48, 31
	s_add_i32 s14, s41, s50
	s_add_i32 s41, s41, s40
	s_ashr_i32 s47, s46, 31
	v_lshl_add_u32 v184, v13, 3, s41
	s_lshl_b64 s[80:81], s[48:49], 1
	v_readlane_b32 s40, v252, 17
	v_readlane_b32 s41, v252, 18
	s_add_u32 s40, s40, s80
	s_addc_u32 s41, s41, s81
	v_lshlrev_b32_e32 v16, 4, v8
	v_add_u32_e32 v163, 0, v16
	v_mul_f32_e32 v136, 0x41800000, v134
	v_writelane_b32 v255, s14, 13
	s_mulk_i32 s23, 0x820
	v_cmp_eq_u32_e64 s[38:39], 0, v8
	v_mul_u32_u24_e32 v165, 0x90, v13
	v_mul_u32_u24_e32 v168, 0x98, v13
	v_add_u32_e32 v171, 0x9400, v163
	v_add3_u32 v177, 0, v176, v164
	v_or_b32_e32 v132, 16, v130
	v_cmp_eq_u32_e64 s[44:45], 0, v129
	s_waitcnt vmcnt(0) lgkmcnt(0)
; __device__ __forceinline__ float wave_max64(float v) {
; #pragma unroll
;     for (int o = 1; o < 64; o <<= 1) v = fmaxf(v, __shfl_xor(v, o));
;     return v;
; }
; __device__ __forceinline__ void nsa_phase(const Args& a, int l, int qslot, LAS unsigned char* lds, int tid, int lane, int wave) {
;     ...
;     const float qmx = wave_max64(fabsf(INTAB(a)[20][l * 64 + lane]));
;     const float bnd0 = 11.72f * qmx * wave_max64(fabsf(INTAB(a)[21][l * 192 + lane])), bnd1 = 11.72f * qmx * wave_max64(fabsf(INTAB(a)[21][l * 192 + 64 + lane])), bnd2 = 11.72f * qmx * wave_max64(fabsf(INTAB(a)[21][l * 192 + 128 + lane]));
	v_and_b32_e32 v0, 0x7fffffff, v14
	v_max_f32_e64 v11, |v14|, |v14|
	ds_bpermute_b32 v0, v17, v0
	v_and_b32_e32 v14, 0x7fffffff, v15
	ds_bpermute_b32 v14, v17, v14
	v_and_b32_e32 v21, 0x7fffffff, v12
	ds_bpermute_b32 v21, v17, v21
	v_and_b32_e32 v23, 0x7fffffff, v10
	ds_bpermute_b32 v17, v17, v23
	v_max_f32_e64 v15, |v15|, |v15|
	s_waitcnt lgkmcnt(3)
	v_max_f32_e32 v0, v0, v0
	s_waitcnt lgkmcnt(2)
	v_max_f32_e32 v14, v14, v14
	v_max_f32_e64 v12, |v12|, |v12|
	v_max_f32_e64 v10, |v10|, |v10|
	v_max_f32_e32 v0, v11, v0
	v_max_f32_e32 v11, v15, v14
	s_waitcnt lgkmcnt(1)
	v_max_f32_e32 v14, v21, v21
	s_waitcnt lgkmcnt(0)
	v_max_f32_e32 v15, v17, v17
	ds_bpermute_b32 v17, v9, v0
	v_max_f32_e32 v12, v12, v14
	v_max_f32_e32 v10, v10, v15
	ds_bpermute_b32 v21, v9, v11
	ds_bpermute_b32 v14, v9, v12
	ds_bpermute_b32 v9, v9, v10
	s_waitcnt lgkmcnt(3)
	v_max_f32_e32 v15, v17, v17
	v_max_f32_e32 v0, v0, v15
	s_waitcnt lgkmcnt(2)
	v_max_f32_e32 v17, v21, v21
	s_waitcnt lgkmcnt(1)
	v_max_f32_e32 v14, v14, v14
	s_waitcnt lgkmcnt(0)
	v_max_f32_e32 v9, v9, v9
	v_max_f32_e32 v11, v11, v17
	ds_bpermute_b32 v15, v18, v0
	v_max_f32_e32 v12, v12, v14
	v_max_f32_e32 v9, v10, v9
	ds_bpermute_b32 v17, v18, v11
	ds_bpermute_b32 v10, v18, v12
	ds_bpermute_b32 v14, v18, v9
	s_waitcnt lgkmcnt(3)
	v_max_f32_e32 v15, v15, v15
	v_max_f32_e32 v0, v0, v15
	s_waitcnt lgkmcnt(2)
	v_max_f32_e32 v17, v17, v17
	s_waitcnt lgkmcnt(1)
	v_max_f32_e32 v10, v10, v10
	s_waitcnt lgkmcnt(0)
	v_max_f32_e32 v14, v14, v14
	v_max_f32_e32 v11, v11, v17
	ds_bpermute_b32 v15, v19, v0
	v_max_f32_e32 v10, v12, v10
	v_max_f32_e32 v9, v9, v14
	ds_bpermute_b32 v17, v19, v11
	ds_bpermute_b32 v12, v19, v10
	ds_bpermute_b32 v14, v19, v9
	s_waitcnt lgkmcnt(3)
	v_max_f32_e32 v15, v15, v15
	v_max_f32_e32 v0, v0, v15
	s_waitcnt lgkmcnt(2)
	v_max_f32_e32 v17, v17, v17
	s_waitcnt lgkmcnt(1)
	v_max_f32_e32 v12, v12, v12
	s_waitcnt lgkmcnt(0)
	v_max_f32_e32 v14, v14, v14
	v_max_f32_e32 v11, v11, v17
	ds_bpermute_b32 v15, v139, v0
	v_max_f32_e32 v10, v10, v12
	v_max_f32_e32 v9, v9, v14
	ds_bpermute_b32 v17, v139, v11
	ds_bpermute_b32 v12, v139, v10
	ds_bpermute_b32 v14, v139, v9
	s_waitcnt lgkmcnt(3)
	v_max_f32_e32 v15, v15, v15
	v_max_f32_e32 v0, v0, v15
	s_waitcnt lgkmcnt(2)
	v_max_f32_e32 v17, v17, v17
	s_waitcnt lgkmcnt(1)
	v_max_f32_e32 v12, v12, v12
	s_waitcnt lgkmcnt(0)
	v_max_f32_e32 v14, v14, v14
	v_max_f32_e32 v11, v11, v17
	ds_bpermute_b32 v15, v162, v0
	v_max_f32_e32 v10, v10, v12
	v_max_f32_e32 v9, v9, v14
	ds_bpermute_b32 v17, v162, v11
	ds_bpermute_b32 v12, v162, v10
	ds_bpermute_b32 v14, v162, v9
	s_waitcnt lgkmcnt(3)
	v_max_f32_e32 v15, v15, v15
	v_max_f32_e32 v0, v0, v15
	s_waitcnt lgkmcnt(2)
	v_max_f32_e32 v17, v17, v17
	s_waitcnt lgkmcnt(1)
	v_max_f32_e32 v12, v12, v12
	s_waitcnt lgkmcnt(0)
	v_max_f32_e32 v14, v14, v14
	v_max_f32_e32 v11, v11, v17
	v_mul_f32_e32 v0, 0x413b851f, v0
	v_max_f32_e32 v10, v10, v12
	v_max_f32_e32 v9, v9, v14
	v_mul_f32_e32 v181, v0, v11
	v_mul_f32_e32 v182, v0, v10
	v_mul_f32_e32 v183, v0, v9
	v_and_b32_e32 v0, 48, v8
	v_lshl_add_u64 v[140:141], s[40:41], 0, v[0:1]
	s_lshl_b64 s[40:41], s[46:47], 2
	s_add_u32 s82, s60, s40
	s_addc_u32 s83, s61, s41
	s_andn2_b32 s15, s15, 63
	v_lshlrev_b64 v[10:11], v8, -1
	s_add_i32 s40, 0, 0x9400
	s_add_i32 s14, s15, 0x19800
	v_not_b32_e32 v127, v11
	v_not_b32_e32 v138, v10
	v_mov_b32_e32 v142, v136
	v_mov_b32_e32 v143, v136
	v_mov_b32_e32 v144, v136
	v_mov_b32_e32 v145, v136
	v_mov_b32_e32 v146, v134
	v_mov_b32_e32 v147, v134
	v_mov_b32_e32 v148, v134
	v_mov_b32_e32 v149, v134
	v_add_u32_e32 v185, s40, v16
	v_writelane_b32 v255, s14, 14
	v_add_u32_e32 v187, s23, v22
	s_branch .LBB0_132

; __device__ __forceinline__ void nsa_phase(const Args& a, int l, int qslot, LAS unsigned char* lds, int tid, int lane, int wave) {
;     ...
;         if (u >= 512) break;
;         const int b = u & 7, qi = 63 - (u >> 3);
;         nsa_unit(a, l, b, qi, bnd0, bnd1, bnd2, lds, tid, lane, wave);
;     }
; }
.LBB0_310:
	s_setprio 0
	s_mov_b64 s[38:39], 0
	s_mov_b32 s9, 0x6000000
	s_movk_i32 s14, 0x1000
	s_movk_i32 s75, 0x1600
	s_mov_b32 s78, 0x6001000
	v_readlane_b32 s79, v254, 43
	s_mov_b32 s6, 0x2aaaaaab
	v_readlane_b32 s7, v255, 6
	v_readlane_b32 s69, v255, 8
	v_readlane_b32 s74, v255, 7
	s_mov_b64 s[42:43], 0
	s_mov_b64 s[82:83], s[70:71]
